# hg_seq_job: prefetch distance two chunks (two landing register sets, loop unrolled by two)
# baseline (speedup 1.0000x reference)
.LBB0_579:
	s_or_b64 exec, exec, s[8:9]
	s_lshl_b32 s8, s30, 7
	s_lshl_b32 s9, s34, 5
	s_add_i32 s12, s8, s9
	s_ashr_i32 s13, s12, 31
	v_readlane_b32 s24, v251, 28
	s_lshl_b64 s[14:15], s[12:13], 6
	v_readlane_b32 s25, v251, 29
	v_and_b32_e32 v42, 15, v14
	v_ashrrev_i32_e32 v0, 4, v14
	s_or_b64 s[8:9], s[14:15], s[24:25]
	v_or_b32_e32 v2, s8, v42
	v_mov_b32_e32 v3, s9
	v_lshlrev_b32_e32 v16, 3, v0
	v_lshlrev_b64 v[2:3], 8, v[2:3]
	v_ashrrev_i32_e32 v17, 31, v16
	v_lshl_add_u64 v[2:3], s[6:7], 0, v[2:3]
	v_lshlrev_b64 v[18:19], 1, v[16:17]
	v_lshl_add_u64 v[2:3], v[2:3], 0, v[18:19]
	s_mov_b64 s[8:9], 0x16588000
	v_lshl_add_u64 v[4:5], v[2:3], 0, s[8:9]
	s_mov_b32 s8, 0x16588000
	v_add_co_u32_e32 v2, vcc, s8, v2
	s_lshl_b32 s20, s28, 1
	v_readlane_b32 s8, v252, 41
	s_add_i32 s72, s8, s20
	s_lshl_b64 s[8:9], s[12:13], 15
	s_lshl_b64 s[10:11], s[72:73], 10
	s_add_u32 s16, s6, s8
	s_addc_u32 s17, s7, s9
	v_ashrrev_i32_e32 v15, 31, v14
	s_add_u32 s16, s16, s10
	s_addc_u32 s17, s17, s11
	v_lshlrev_b64 v[20:21], 4, v[14:15]
	v_addc_co_u32_e32 v3, vcc, 0, v3, vcc
	v_lshl_add_u64 v[6:7], s[16:17], 0, v[20:21]
	s_mov_b32 s16, 0x17588000
	v_add_co_u32_e32 v6, vcc, s16, v6
	v_readlane_b32 s16, v252, 60
	s_add_i32 s72, s20, s16
	s_add_u32 s14, s14, s72
	s_addc_u32 s15, s15, 0
	v_lshlrev_b64 v[22:23], 3, v[14:15]
	v_lshl_add_u64 v[8:9], s[6:7], 0, v[22:23]
	s_lshl_b64 s[14:15], s[14:15], 9
	v_lshl_add_u64 v[8:9], v[8:9], 0, s[14:15]
	s_mov_b64 s[14:15], 0x19588000
	v_addc_co_u32_e32 v7, vcc, 0, v7, vcc
	v_lshl_add_u64 v[24:25], v[8:9], 0, s[14:15]
	s_mov_b32 s14, 0x19588000
	s_lshl_b64 s[16:17], s[12:13], 9
	v_add_co_u32_e32 v8, vcc, s14, v8
	s_add_u32 s14, s6, s16
	v_readlane_b32 s20, v252, 55
	s_addc_u32 s15, s7, s17
	s_lshl_b32 s20, s20, 2
	v_lshlrev_b32_e32 v44, 2, v0
	v_addc_co_u32_e32 v9, vcc, 0, v9, vcc
	s_add_u32 s14, s14, s20
	v_ashrrev_i32_e32 v45, 31, v44
	global_load_dwordx4 v[26:29], v[4:5], off offset:64
	global_load_dwordx4 v[34:37], v[4:5], off offset:128
	global_load_dwordx4 v[30:33], v[2:3], off
	s_nop 0
	global_load_dwordx4 v[2:5], v[4:5], off offset:192
	s_nop 0
	global_load_dwordx2 v[48:49], v[8:9], off
	global_load_dwordx4 v[10:13], v[6:7], off
	global_load_dwordx2 v[46:47], v[24:25], off offset:512
	s_addc_u32 s15, s15, 0
	v_lshlrev_b64 v[24:25], 2, v[44:45]
	v_lshl_add_u64 v[6:7], s[14:15], 0, v[24:25]
	s_mov_b32 s14, 0x1b588000
	v_add_co_u32_e32 v6, vcc, s14, v6
	s_ashr_i32 s31, s30, 31
	s_nop 0
	v_addc_co_u32_e32 v7, vcc, 0, v7, vcc
	global_load_dwordx4 v[6:9], v[6:7], off
	v_readlane_b32 s15, v252, 42
	s_lshl_b64 s[20:21], s[30:31], 11
	s_lshl_b64 s[22:23], s[72:73], 9
	s_lshl_b64 s[12:13], s[12:13], 14
	v_or_b32_e32 v0, s15, v42
	s_movk_i32 s15, 0x110
	s_add_u32 s12, s12, 0x1658c080
	v_mul_lo_u32 v0, v0, s15
	v_and_b32_e32 v14, -16, v14
	s_addc_u32 s13, s13, 0
	v_add3_u32 v72, 0, v0, v14
	v_mul_u32_u24_e32 v0, 0x110, v42
	v_readlane_b32 s15, v251, 32
	v_lshl_add_u64 v[14:15], s[12:13], 0, v[18:19]
	v_readlane_b32 s12, v252, 33
	v_add3_u32 v43, s15, v16, v0
	s_mov_b32 s35, s73
	v_lshl_add_u32 v0, v42, 8, s12
	s_or_b64 s[12:13], s[24:25], s[20:21]
	s_mov_b32 s29, s73
	v_lshl_add_u64 v[50:51], s[12:13], 0, v[44:45]
	s_lshl_b64 s[12:13], s[34:35], 8
	s_lshl_b64 s[20:21], s[28:29], 6
	s_add_u32 s12, s20, s12
	s_addc_u32 s13, s21, s13
	v_readlane_b32 s15, v251, 20
	s_add_u32 s12, s12, s15
	s_addc_u32 s13, s13, 0
	v_lshl_add_u64 v[60:61], v[14:15], 0, v[0:1]
	v_mov_b64_e32 v[14:15], s[12:13]
	v_mad_u64_u32 v[14:15], s[12:13], v50, s49, v[14:15]
	v_readlane_b32 s12, v251, 23
	s_add_u32 s12, s12, s16
	v_readlane_b32 s13, v251, 24
	s_addc_u32 s13, s13, s17
	v_mad_i32_i24 v15, v51, s49, v15
	v_lshl_add_u64 v[64:65], s[12:13], 0, v[24:25]
	s_add_u32 s12, s8, s22
	s_addc_u32 s13, s9, s23
	s_add_u32 s8, s8, s10
	s_addc_u32 s9, s9, s11
	s_add_u32 s8, s8, 0x17590000
	v_lshlrev_b32_e32 v0, 1, v42
	s_addc_u32 s9, s9, 0
	v_mov_b32_e32 v52, 0
	s_mov_b32 s14, 0
	v_lshl_add_u64 v[62:63], v[14:15], 0, v[0:1]
	v_lshl_add_u64 v[66:67], s[12:13], 0, v[22:23]
	v_lshl_add_u64 v[68:69], s[8:9], 0, v[20:21]
	v_mov_b32_e32 v53, v52
	v_mov_b32_e32 v58, v52
	v_mov_b32_e32 v59, v52
	v_mov_b32_e32 v54, v52
	v_mov_b32_e32 v55, v52
	v_mov_b32_e32 v56, v52
	v_mov_b32_e32 v57, v52
	s_mov_b32 s12, 0xe8c1000
	s_mov_b32 s13, 0xe8c2000
	s_mov_b64 s[16:17], 0x4000
	s_mov_b64 s[20:21], 0x8000
	v_lshl_add_u64 v[124:125], s[6:7], 0, v[60:61]
	v_lshl_add_u64 v[126:127], s[6:7], 0, v[68:69]
	global_load_dword v128, v[124:125], off
	global_load_dword v128, v[124:125], off
	global_load_dword v128, v[124:125], off
	global_load_dword v128, v[124:125], off
	global_load_dwordx4 v[96:99], v[124:125], off offset:-128
	global_load_dwordx4 v[100:103], v[124:125], off offset:-64
	global_load_dwordx4 v[104:107], v[124:125], off
	global_load_dwordx4 v[108:111], v[124:125], off offset:64
	global_load_dwordx4 v[112:115], v[126:127], off
	v_lshl_add_u64 v[126:127], s[6:7], 0, v[66:67]
	s_mov_b32 s9, 0x19590000
	v_add_co_u32_e32 v126, vcc, s9, v126
	s_nop 1
	v_addc_co_u32_e32 v127, vcc, 0, v127, vcc
	global_load_dwordx2 v[116:117], v[126:127], off
	global_load_dwordx2 v[118:119], v[126:127], off offset:512
	v_lshl_add_u64 v[126:127], s[6:7], 0, v[64:65]
	global_load_dwordx4 v[120:123], v[126:127], off
	global_load_dword v128, v[124:125], off
	global_load_dword v128, v[124:125], off
	global_load_dword v128, v[124:125], off
	global_load_dword v128, v[124:125], off
	v_lshl_add_u64 v[60:61], v[60:61], 0, s[16:17]
	v_lshl_add_u64 v[64:65], v[64:65], 0, s[50:51]
	v_lshl_add_u64 v[66:67], v[66:67], 0, s[20:21]
	v_lshl_add_u64 v[68:69], v[68:69], 0, s[20:21]
	s_waitcnt lgkmcnt(0)
	s_barrier
	s_waitcnt vmcnt(16)
	v_mov_b32_e32 v45, v48
	s_waitcnt vmcnt(16)
	v_mov_b32_e32 v0, v46
.LBB0_580:
	v_mov_b64_e32 v[76:77], v[4:5]
	s_waitcnt vmcnt(16)
	v_mov_b64_e32 v[40:41], v[8:9]
	v_mov_b64_e32 v[74:75], v[2:3]
	v_mov_b64_e32 v[38:39], v[6:7]
	v_mov_b64_e32 v[80:81], v[12:13]
	v_lshl_add_u64 v[2:3], s[6:7], 0, v[60:61]
	v_lshl_add_u64 v[6:7], s[6:7], 0, v[68:69]
	v_mov_b64_e32 v[78:79], v[10:11]
	global_load_dwordx4 v[22:25], v[2:3], off offset:-128
	global_load_dwordx4 v[18:21], v[2:3], off offset:-64
	global_load_dwordx4 v[14:17], v[2:3], off
	s_nop 0
	global_load_dwordx4 v[2:5], v[2:3], off offset:64
	s_mov_b32 s9, 0x19590000
	global_load_dwordx4 v[10:13], v[6:7], off
	v_lshl_add_u64 v[6:7], s[6:7], 0, v[66:67]
	v_add_co_u32_e32 v6, vcc, s9, v6
	v_mov_b64_e32 v[70:71], v[46:47]
	s_nop 0
	v_addc_co_u32_e32 v7, vcc, 0, v7, vcc
	v_mov_b64_e32 v[86:87], v[48:49]
	global_load_dwordx2 v[48:49], v[6:7], off
	global_load_dwordx2 v[46:47], v[6:7], off offset:512
	v_lshl_add_u64 v[6:7], s[6:7], 0, v[64:65]
	global_load_dwordx4 v[6:9], v[6:7], off
	s_add_i32 s8, s14, 1
	s_bitcmp1_b32 s14, 0
	s_cselect_b32 s9, 0x2200, 0
	v_add_u32_e32 v70, s9, v72
	ds_read_b128 v[82:85], v70
	s_waitcnt lgkmcnt(0)
	v_mfma_f32_16x16x32_bf16 v[30:33], v[30:33], v[82:85], v[78:81]
	s_nop 2
	ds_read_b128 v[78:81], v70 offset:64
	s_bitcmp1_b32 s8, 0
	s_cselect_b32 s9, 0x2200, 0
	s_waitcnt lgkmcnt(0)
	v_mfma_f32_16x16x32_bf16 v[26:29], v[26:29], v[78:81], v[30:33]
	s_mov_b64 s[10:11], 0x30000
	s_nop 1
	ds_read_b128 v[30:33], v70 offset:128
	v_lshl_add_u64 v[60:61], v[60:61], 0, s[16:17]
	s_waitcnt lgkmcnt(0)
	v_mfma_f32_16x16x32_bf16 v[26:29], v[34:37], v[30:33], v[26:29]
	ds_read_b128 v[30:33], v70 offset:192
	v_lshl_add_u64 v[64:65], v[64:65], 0, s[50:51]
	v_lshl_add_u64 v[66:67], v[66:67], 0, s[20:21]
	s_waitcnt lgkmcnt(0)
	v_mfma_f32_16x16x32_bf16 v[26:29], v[74:77], v[30:33], v[26:29]
	v_lshl_add_u64 v[68:69], v[68:69], 0, s[20:21]
	s_cmp_lg_u32 s8, 31
	s_mov_b32 s14, s8
	s_nop 4
	v_bfe_u32 v30, v26, 16, 1
	v_add3_u32 v26, v26, v30, s78
	v_lshl_add_u64 v[30:31], s[6:7], 0, v[62:63]
	v_add_co_u32_e32 v32, vcc, s81, v30
	v_lshl_add_u64 v[62:63], v[62:63], 0, s[10:11]
	s_nop 0
	v_addc_co_u32_e32 v33, vcc, 0, v31, vcc
	global_store_short_d16_hi v[32:33], v26, off offset:1024
	v_bfe_u32 v26, v27, 16, 1
	v_add3_u32 v32, v27, v26, s78
	v_add_co_u32_e32 v26, vcc, s12, v30
	s_waitcnt vmcnt(13)
	v_mov_b32_e32 v33, v99
	v_addc_co_u32_e32 v27, vcc, 0, v31, vcc
	global_store_short_d16_hi v[26:27], v32, off
	v_bfe_u32 v32, v28, 16, 1
	v_add3_u32 v28, v28, v32, s78
	global_store_short_d16_hi v[26:27], v28, off offset:3072
	v_bfe_u32 v26, v29, 16, 1
	v_add3_u32 v28, v29, v26, s78
	v_add_co_u32_e32 v26, vcc, s13, v30
	v_and_b32_e32 v29, 0xffff0000, v87
	s_nop 0
	v_addc_co_u32_e32 v27, vcc, 0, v31, vcc
	global_store_short_d16_hi v[26:27], v28, off offset:2048
	v_lshlrev_b32_e32 v26, 16, v45
	v_and_b32_e32 v27, 0xffff0000, v45
	v_lshlrev_b32_e32 v28, 16, v87
	v_pk_fma_f32 v[58:59], v[40:41], v[58:59], v[28:29]
	v_pk_fma_f32 v[52:53], v[38:39], v[52:53], v[26:27]
	v_cvt_pk_bf16_f32 v27, v58, v59
	v_cvt_pk_bf16_f32 v26, v52, v53
	v_add_u32_e32 v30, s9, v43
	ds_write_b64 v30, v[26:27]
	v_lshlrev_b32_e32 v26, 16, v0
	v_and_b32_e32 v27, 0xffff0000, v0
	v_lshlrev_b32_e32 v28, 16, v71
	v_and_b32_e32 v29, 0xffff0000, v71
	v_pk_fma_f32 v[56:57], v[40:41], v[56:57], v[28:29]
	v_pk_fma_f32 v[54:55], v[38:39], v[54:55], v[26:27]
	v_cvt_pk_bf16_f32 v27, v56, v57
	v_cvt_pk_bf16_f32 v26, v54, v55
	ds_write_b64 v30, v[26:27] offset:4352
	v_mov_b32_e32 v30, v96
	v_mov_b32_e32 v31, v97
	v_mov_b32_e32 v32, v98
	s_waitcnt vmcnt(16)
	v_mov_b32_e32 v26, v100
	v_mov_b32_e32 v27, v101
	v_mov_b32_e32 v28, v102
	v_mov_b32_e32 v29, v103
	s_waitcnt vmcnt(16)
	v_mov_b32_e32 v34, v104
	v_mov_b32_e32 v35, v105
	v_mov_b32_e32 v36, v106
	v_mov_b32_e32 v37, v107
	s_waitcnt vmcnt(16)
	v_mov_b32_e32 v45, v116
	s_waitcnt vmcnt(16)
	v_mov_b32_e32 v0, v118
	s_waitcnt lgkmcnt(0)
	s_barrier
	s_cbranch_scc1 .Lhgs_odd
	s_branch .Lhgs_fix
.Lhgs_odd:
	v_mov_b64_e32 v[76:77], v[110:111]
	s_waitcnt vmcnt(16)
	v_mov_b64_e32 v[40:41], v[122:123]
	v_mov_b64_e32 v[74:75], v[108:109]
	v_mov_b64_e32 v[38:39], v[120:121]
	v_mov_b64_e32 v[80:81], v[114:115]
	v_lshl_add_u64 v[124:125], s[6:7], 0, v[60:61]
	v_lshl_add_u64 v[126:127], s[6:7], 0, v[68:69]
	v_mov_b64_e32 v[78:79], v[112:113]
	global_load_dwordx4 v[96:99], v[124:125], off offset:-128
	global_load_dwordx4 v[100:103], v[124:125], off offset:-64
	global_load_dwordx4 v[104:107], v[124:125], off
	s_nop 0
	global_load_dwordx4 v[108:111], v[124:125], off offset:64
	s_mov_b32 s9, 0x19590000
	global_load_dwordx4 v[112:115], v[126:127], off
	v_lshl_add_u64 v[126:127], s[6:7], 0, v[66:67]
	v_add_co_u32_e32 v126, vcc, s9, v126
	v_mov_b64_e32 v[70:71], v[118:119]
	s_nop 0
	v_addc_co_u32_e32 v127, vcc, 0, v127, vcc
	v_mov_b64_e32 v[86:87], v[116:117]
	global_load_dwordx2 v[116:117], v[126:127], off
	global_load_dwordx2 v[118:119], v[126:127], off offset:512
	v_lshl_add_u64 v[126:127], s[6:7], 0, v[64:65]
	global_load_dwordx4 v[120:123], v[126:127], off
	s_add_i32 s8, s14, 1
	s_bitcmp1_b32 s14, 0
	s_cselect_b32 s9, 0x2200, 0
	v_add_u32_e32 v70, s9, v72
	ds_read_b128 v[82:85], v70
	s_waitcnt lgkmcnt(0)
	v_mfma_f32_16x16x32_bf16 v[30:33], v[30:33], v[82:85], v[78:81]
	s_nop 2
	ds_read_b128 v[78:81], v70 offset:64
	s_bitcmp1_b32 s8, 0
	s_cselect_b32 s9, 0x2200, 0
	s_waitcnt lgkmcnt(0)
	v_mfma_f32_16x16x32_bf16 v[26:29], v[26:29], v[78:81], v[30:33]
	s_mov_b64 s[10:11], 0x30000
	s_nop 1
	ds_read_b128 v[30:33], v70 offset:128
	v_lshl_add_u64 v[60:61], v[60:61], 0, s[16:17]
	s_waitcnt lgkmcnt(0)
	v_mfma_f32_16x16x32_bf16 v[26:29], v[34:37], v[30:33], v[26:29]
	ds_read_b128 v[30:33], v70 offset:192
	v_lshl_add_u64 v[64:65], v[64:65], 0, s[50:51]
	v_lshl_add_u64 v[66:67], v[66:67], 0, s[20:21]
	s_waitcnt lgkmcnt(0)
	v_mfma_f32_16x16x32_bf16 v[26:29], v[74:77], v[30:33], v[26:29]
	v_lshl_add_u64 v[68:69], v[68:69], 0, s[20:21]
	s_cmp_lg_u32 s8, 31
	s_mov_b32 s14, s8
	s_nop 4
	v_bfe_u32 v30, v26, 16, 1
	v_add3_u32 v26, v26, v30, s78
	v_lshl_add_u64 v[30:31], s[6:7], 0, v[62:63]
	v_add_co_u32_e32 v32, vcc, s81, v30
	v_lshl_add_u64 v[62:63], v[62:63], 0, s[10:11]
	s_nop 0
	v_addc_co_u32_e32 v33, vcc, 0, v31, vcc
	global_store_short_d16_hi v[32:33], v26, off offset:1024
	v_bfe_u32 v26, v27, 16, 1
	v_add3_u32 v32, v27, v26, s78
	v_add_co_u32_e32 v26, vcc, s12, v30
	s_waitcnt vmcnt(13)
	v_mov_b32_e32 v33, v25
	v_addc_co_u32_e32 v27, vcc, 0, v31, vcc
	global_store_short_d16_hi v[26:27], v32, off
	v_bfe_u32 v32, v28, 16, 1
	v_add3_u32 v28, v28, v32, s78
	global_store_short_d16_hi v[26:27], v28, off offset:3072
	v_bfe_u32 v26, v29, 16, 1
	v_add3_u32 v28, v29, v26, s78
	v_add_co_u32_e32 v26, vcc, s13, v30
	v_and_b32_e32 v29, 0xffff0000, v87
	s_nop 0
	v_addc_co_u32_e32 v27, vcc, 0, v31, vcc
	global_store_short_d16_hi v[26:27], v28, off offset:2048
	v_lshlrev_b32_e32 v26, 16, v45
	v_and_b32_e32 v27, 0xffff0000, v45
	v_lshlrev_b32_e32 v28, 16, v87
	v_pk_fma_f32 v[58:59], v[40:41], v[58:59], v[28:29]
	v_pk_fma_f32 v[52:53], v[38:39], v[52:53], v[26:27]
	v_cvt_pk_bf16_f32 v27, v58, v59
	v_cvt_pk_bf16_f32 v26, v52, v53
	v_add_u32_e32 v30, s9, v43
	ds_write_b64 v30, v[26:27]
	v_lshlrev_b32_e32 v26, 16, v0
	v_and_b32_e32 v27, 0xffff0000, v0
	v_lshlrev_b32_e32 v28, 16, v71
	v_and_b32_e32 v29, 0xffff0000, v71
	v_pk_fma_f32 v[56:57], v[40:41], v[56:57], v[28:29]
	v_pk_fma_f32 v[54:55], v[38:39], v[54:55], v[26:27]
	v_cvt_pk_bf16_f32 v27, v56, v57
	v_cvt_pk_bf16_f32 v26, v54, v55
	ds_write_b64 v30, v[26:27] offset:4352
	v_mov_b32_e32 v30, v22
	v_mov_b32_e32 v31, v23
	v_mov_b32_e32 v32, v24
	s_waitcnt vmcnt(16)
	v_mov_b32_e32 v26, v18
	v_mov_b32_e32 v27, v19
	v_mov_b32_e32 v28, v20
	v_mov_b32_e32 v29, v21
	s_waitcnt vmcnt(16)
	v_mov_b32_e32 v34, v14
	v_mov_b32_e32 v35, v15
	v_mov_b32_e32 v36, v16
	v_mov_b32_e32 v37, v17
	s_waitcnt vmcnt(16)
	v_mov_b32_e32 v45, v48
	s_waitcnt vmcnt(16)
	v_mov_b32_e32 v0, v46
	s_waitcnt lgkmcnt(0)
	s_barrier
	s_cbranch_scc1 .LBB0_580
	s_branch .Lhgs_tail
.Lhgs_fix:
	s_waitcnt vmcnt(0)
	v_mov_b32_e32 v2, v108
	v_mov_b32_e32 v3, v109
	v_mov_b32_e32 v4, v110
	v_mov_b32_e32 v5, v111
	v_mov_b32_e32 v6, v120
	v_mov_b32_e32 v7, v121
	v_mov_b32_e32 v8, v122
	v_mov_b32_e32 v9, v123
	v_mov_b32_e32 v10, v112
	v_mov_b32_e32 v11, v113
	v_mov_b32_e32 v12, v114
	v_mov_b32_e32 v13, v115
	v_mov_b32_e32 v14, v104
	v_mov_b32_e32 v15, v105
	v_mov_b32_e32 v16, v106
	v_mov_b32_e32 v17, v107
	v_mov_b32_e32 v18, v100
	v_mov_b32_e32 v19, v101
	v_mov_b32_e32 v20, v102
	v_mov_b32_e32 v21, v103
	v_mov_b32_e32 v22, v96
	v_mov_b32_e32 v23, v97
	v_mov_b32_e32 v24, v98
	v_mov_b32_e32 v25, v99
	v_mov_b32_e32 v46, v118
	v_mov_b32_e32 v47, v119
	v_mov_b32_e32 v48, v116
	v_mov_b32_e32 v49, v117
.Lhgs_tail:
	ds_read_b128 v[26:29], v72 offset:8768
	ds_read_b128 v[30:33], v72 offset:8704
	s_lshl_b32 s72, s28, 5
	s_lshl_b32 s8, s34, 8
	s_add_u32 s6, s6, s8
	s_addc_u32 s7, s7, 0
	s_waitcnt lgkmcnt(0)
	v_mfma_f32_16x16x32_bf16 v[10:13], v[22:25], v[30:33], v[10:13]
	ds_read_b128 v[22:25], v72 offset:8896
	ds_read_b128 v[30:33], v72 offset:8832
	s_lshl_b32 s8, s28, 6
	s_add_u32 s6, s6, s8
	v_mfma_f32_16x16x32_bf16 v[10:13], v[18:21], v[26:29], v[10:13]
	v_readlane_b32 s8, v252, 42
	s_addc_u32 s7, s7, 0
	s_lshl_b32 s8, s8, 1
	s_waitcnt lgkmcnt(0)
	v_mfma_f32_16x16x32_bf16 v[10:13], v[14:17], v[30:33], v[10:13]
	s_add_u32 s6, s6, s8
	s_addc_u32 s7, s7, 0
	v_lshlrev_b32_e32 v0, 1, v42
	v_lshl_add_u64 v[14:15], s[6:7], 0, v[0:1]
	s_mov_b64 s[6:7], 0xe8c0400
	v_mfma_f32_16x16x32_bf16 v[2:5], v[2:5], v[22:25], v[10:13]
	v_lshl_add_u64 v[14:15], v[14:15], 0, s[6:7]
	s_lshl_b64 s[8:9], s[34:35], 16
	s_nop 0
	v_mad_u64_u32 v[10:11], s[6:7], v50, s49, v[14:15]
	s_mov_b32 s6, 0x5d0000
	s_nop 2
	v_bfe_u32 v0, v2, 16, 1
	v_mad_i32_i24 v11, v51, s49, v11
	v_add_co_u32_e32 v12, vcc, s6, v10
	v_add3_u32 v0, v2, v0, s78
	s_nop 0
	v_addc_co_u32_e32 v13, vcc, 0, v11, vcc
	global_store_short_d16_hi v[12:13], v0, off
	v_bfe_u32 v0, v3, 16, 1
	v_add3_u32 v0, v3, v0, s78
	s_mov_b32 s6, 0x5d1000
	global_store_short_d16_hi v[12:13], v0, off offset:3072
	v_bfe_u32 v0, v4, 16, 1
	v_add_co_u32_e32 v2, vcc, s6, v10
	v_add3_u32 v0, v4, v0, s78
	s_nop 0
	v_addc_co_u32_e32 v3, vcc, 0, v11, vcc
	s_mov_b32 s6, 0x5d2000
	global_store_short_d16_hi v[2:3], v0, off offset:2048
	v_bfe_u32 v0, v5, 16, 1
	v_add_co_u32_e32 v2, vcc, s6, v10
	v_add3_u32 v0, v5, v0, s78
	s_nop 0
	v_addc_co_u32_e32 v3, vcc, 0, v11, vcc
	global_store_short_d16_hi v[2:3], v0, off offset:1024
	v_lshlrev_b32_e32 v2, 16, v48
	v_and_b32_e32 v3, 0xffff0000, v48
	v_lshlrev_b32_e32 v4, 16, v49
	v_and_b32_e32 v5, 0xffff0000, v49
	s_waitcnt vmcnt(8)
	v_pk_fma_f32 v[4:5], v[8:9], v[58:59], v[4:5]
	v_pk_fma_f32 v[2:3], v[6:7], v[52:53], v[2:3]
	v_cvt_pk_bf16_f32 v11, v4, v5
	v_cvt_pk_bf16_f32 v10, v2, v3
	ds_write_b64 v43, v[10:11]
	v_lshlrev_b32_e32 v10, 16, v46
	v_and_b32_e32 v11, 0xffff0000, v46
	v_lshlrev_b32_e32 v12, 16, v47
	v_and_b32_e32 v13, 0xffff0000, v47
	v_pk_fma_f32 v[8:9], v[8:9], v[56:57], v[12:13]
	v_pk_fma_f32 v[6:7], v[6:7], v[54:55], v[10:11]
	v_cvt_pk_bf16_f32 v11, v8, v9
	v_cvt_pk_bf16_f32 v10, v6, v7
	ds_write_b64 v43, v[10:11] offset:4352
	s_waitcnt lgkmcnt(0)
	s_barrier
	s_load_dwordx2 s[0:1], s[0:1], 0x150
	s_lshl_b64 s[6:7], s[30:31], 18
	v_lshlrev_b32_e32 v0, 2, v42
	s_waitcnt lgkmcnt(0)
	s_add_u32 s0, s0, s6
	s_addc_u32 s1, s1, s7
	v_readlane_b32 s6, v250, 22
	s_add_u32 s0, s0, s6
	s_addc_u32 s1, s1, 0
	s_add_u32 s6, s0, s8
	v_readlane_b32 s0, v252, 55
	s_addc_u32 s7, s1, s9
	s_nop 0
	v_add_u32_e32 v10, s0, v44
	s_lshl_b64 s[0:1], s[72:73], 2
	s_add_u32 s0, s6, s0
	s_addc_u32 s1, s7, s1
	v_lshl_add_u64 v[12:13], s[0:1], 0, v[0:1]
	s_mov_b64 s[0:1], 0x4220000
	v_ashrrev_i32_e32 v11, 31, v10
	v_or_b32_e32 v16, 1, v10
	v_lshl_add_u64 v[12:13], v[12:13], 0, s[0:1]
	v_lshlrev_b64 v[14:15], 9, v[10:11]
	v_ashrrev_i32_e32 v17, 31, v16
	v_lshl_add_u64 v[14:15], v[12:13], 0, v[14:15]
	v_lshlrev_b64 v[16:17], 9, v[16:17]
	global_store_dword v[14:15], v2, off
	v_lshl_add_u64 v[16:17], v[12:13], 0, v[16:17]
	v_or_b32_e32 v2, 2, v10
	v_or_b32_e32 v10, 3, v10
	global_store_dword v[16:17], v3, off
	v_ashrrev_i32_e32 v3, 31, v2
	v_ashrrev_i32_e32 v11, 31, v10
	v_lshlrev_b64 v[2:3], 9, v[2:3]
	v_lshlrev_b64 v[10:11], 9, v[10:11]
	v_lshl_add_u64 v[2:3], v[12:13], 0, v[2:3]
	v_lshl_add_u64 v[10:11], v[12:13], 0, v[10:11]
	s_mov_b64 s[0:1], 0
	global_store_dword v[2:3], v4, off
	global_store_dword v[10:11], v5, off
	global_store_dword v[14:15], v6, off offset:64
	global_store_dword v[16:17], v7, off offset:64
	global_store_dword v[2:3], v8, off offset:64
	global_store_dword v[10:11], v9, off offset:64
